# triangular substitution runs with only the 32 lanes that own a value column active (no duplicate lanes, half the LDS return traffic)
# speedup vs baseline: 1.0042x; 1.0042x over previous
.Ldc_b2:
	s_waitcnt lgkmcnt(0)
	s_barrier
	s_cmp_ge_u32 s60, 2
	s_cbranch_scc1 .Ldc_s2q
	s_cmp_eq_u32 s60, 1
	s_cbranch_scc1 .Ldc_s2k
	s_mov_b32 exec_hi, 0
	v_and_b32_e32 v135, 31, v221
	v_lshlrev_b32_e32 v135, 2, v135
	ds_read_b32 v10, v135 offset:57856
	ds_read_b32 v11, v135 offset:58000
	ds_read_b32 v12, v135 offset:58144
	ds_read_b32 v13, v135 offset:58288
	ds_read_b32 v14, v135 offset:58432
	ds_read_b32 v15, v135 offset:58576
	ds_read_b32 v16, v135 offset:58720
	ds_read_b32 v17, v135 offset:58864
	ds_read_b32 v18, v135 offset:59008
	ds_read_b32 v19, v135 offset:59152
	ds_read_b32 v20, v135 offset:59296
	ds_read_b32 v21, v135 offset:59440
	ds_read_b32 v22, v135 offset:59584
	ds_read_b32 v23, v135 offset:59728
	ds_read_b32 v24, v135 offset:59872
	ds_read_b32 v25, v135 offset:60016
	ds_read_b32 v26, v135 offset:60160
	ds_read_b32 v27, v135 offset:60304
	ds_read_b32 v28, v135 offset:60448
	ds_read_b32 v29, v135 offset:60592
	ds_read_b32 v30, v135 offset:60736
	ds_read_b32 v31, v135 offset:60880
	ds_read_b32 v32, v135 offset:61024
	ds_read_b32 v33, v135 offset:61168
	ds_read_b32 v34, v135 offset:61312
	ds_read_b32 v35, v135 offset:61456
	ds_read_b32 v36, v135 offset:61600
	ds_read_b32 v37, v135 offset:61744
	ds_read_b32 v38, v135 offset:61888
	ds_read_b32 v39, v135 offset:62032
	ds_read_b32 v40, v135 offset:62176
	ds_read_b32 v41, v135 offset:62320
	ds_read_b128 v[42:45], v1 offset:44032
	ds_read_b128 v[46:49], v1 offset:44048
	ds_read_b128 v[50:53], v1 offset:44064
	ds_read_b128 v[54:57], v1 offset:44080
	ds_read_b128 v[58:61], v1 offset:44096
	ds_read_b128 v[62:65], v1 offset:44112
	ds_read_b128 v[66:69], v1 offset:44128
	ds_read_b128 v[70:73], v1 offset:44144
	ds_read_b128 v[74:77], v1 offset:44176
	ds_read_b128 v[78:81], v1 offset:44192
	ds_read_b128 v[82:85], v1 offset:44208
	ds_read_b128 v[86:89], v1 offset:44224
	ds_read_b128 v[226:229], v1 offset:44240
	ds_read_b128 v[230:233], v1 offset:44256
	ds_read_b128 v[234:237], v1 offset:44272
	ds_read_b128 v[238:241], v1 offset:44288
	s_waitcnt lgkmcnt(0)
	v_fmac_f32_e32 v11, v43, v10
	v_pk_fma_f32 v[12:13], v[44:45], v[10:11], v[12:13] op_sel:[0,0,0] op_sel_hi:[1,0,1]
	v_pk_fma_f32 v[14:15], v[46:47], v[10:11], v[14:15] op_sel:[0,0,0] op_sel_hi:[1,0,1]
	v_pk_fma_f32 v[16:17], v[48:49], v[10:11], v[16:17] op_sel:[0,0,0] op_sel_hi:[1,0,1]
	v_pk_fma_f32 v[18:19], v[50:51], v[10:11], v[18:19] op_sel:[0,0,0] op_sel_hi:[1,0,1]
	v_pk_fma_f32 v[20:21], v[52:53], v[10:11], v[20:21] op_sel:[0,0,0] op_sel_hi:[1,0,1]
	v_pk_fma_f32 v[22:23], v[54:55], v[10:11], v[22:23] op_sel:[0,0,0] op_sel_hi:[1,0,1]
	v_pk_fma_f32 v[24:25], v[56:57], v[10:11], v[24:25] op_sel:[0,0,0] op_sel_hi:[1,0,1]
	v_pk_fma_f32 v[26:27], v[58:59], v[10:11], v[26:27] op_sel:[0,0,0] op_sel_hi:[1,0,1]
	v_pk_fma_f32 v[28:29], v[60:61], v[10:11], v[28:29] op_sel:[0,0,0] op_sel_hi:[1,0,1]
	v_pk_fma_f32 v[30:31], v[62:63], v[10:11], v[30:31] op_sel:[0,0,0] op_sel_hi:[1,0,1]
	v_pk_fma_f32 v[32:33], v[64:65], v[10:11], v[32:33] op_sel:[0,0,0] op_sel_hi:[1,0,1]
	v_pk_fma_f32 v[34:35], v[66:67], v[10:11], v[34:35] op_sel:[0,0,0] op_sel_hi:[1,0,1]
	v_pk_fma_f32 v[36:37], v[68:69], v[10:11], v[36:37] op_sel:[0,0,0] op_sel_hi:[1,0,1]
	v_pk_fma_f32 v[38:39], v[70:71], v[10:11], v[38:39] op_sel:[0,0,0] op_sel_hi:[1,0,1]
	v_pk_fma_f32 v[40:41], v[72:73], v[10:11], v[40:41] op_sel:[0,0,0] op_sel_hi:[1,0,1]
	ds_read_b128 v[42:45], v1 offset:44320
	ds_read_b128 v[46:49], v1 offset:44336
	ds_read_b128 v[50:53], v1 offset:44352
	ds_read_b128 v[54:57], v1 offset:44368
	ds_read_b128 v[58:61], v1 offset:44384
	ds_read_b128 v[62:65], v1 offset:44400
	ds_read_b128 v[66:69], v1 offset:44416
	ds_read_b128 v[70:73], v1 offset:44432
	s_waitcnt lgkmcnt(0)
	v_pk_fma_f32 v[12:13], v[76:77], v[10:11], v[12:13] op_sel:[0,1,0] op_sel_hi:[1,1,1]
	v_pk_fma_f32 v[14:15], v[78:79], v[10:11], v[14:15] op_sel:[0,1,0] op_sel_hi:[1,1,1]
	v_pk_fma_f32 v[16:17], v[80:81], v[10:11], v[16:17] op_sel:[0,1,0] op_sel_hi:[1,1,1]
	v_pk_fma_f32 v[18:19], v[82:83], v[10:11], v[18:19] op_sel:[0,1,0] op_sel_hi:[1,1,1]
	v_pk_fma_f32 v[20:21], v[84:85], v[10:11], v[20:21] op_sel:[0,1,0] op_sel_hi:[1,1,1]
	v_pk_fma_f32 v[22:23], v[86:87], v[10:11], v[22:23] op_sel:[0,1,0] op_sel_hi:[1,1,1]
	v_pk_fma_f32 v[24:25], v[88:89], v[10:11], v[24:25] op_sel:[0,1,0] op_sel_hi:[1,1,1]
	v_pk_fma_f32 v[26:27], v[226:227], v[10:11], v[26:27] op_sel:[0,1,0] op_sel_hi:[1,1,1]
	v_pk_fma_f32 v[28:29], v[228:229], v[10:11], v[28:29] op_sel:[0,1,0] op_sel_hi:[1,1,1]
	v_pk_fma_f32 v[30:31], v[230:231], v[10:11], v[30:31] op_sel:[0,1,0] op_sel_hi:[1,1,1]
	v_pk_fma_f32 v[32:33], v[232:233], v[10:11], v[32:33] op_sel:[0,1,0] op_sel_hi:[1,1,1]
	v_pk_fma_f32 v[34:35], v[234:235], v[10:11], v[34:35] op_sel:[0,1,0] op_sel_hi:[1,1,1]
	v_pk_fma_f32 v[36:37], v[236:237], v[10:11], v[36:37] op_sel:[0,1,0] op_sel_hi:[1,1,1]
	v_pk_fma_f32 v[38:39], v[238:239], v[10:11], v[38:39] op_sel:[0,1,0] op_sel_hi:[1,1,1]
	v_pk_fma_f32 v[40:41], v[240:241], v[10:11], v[40:41] op_sel:[0,1,0] op_sel_hi:[1,1,1]
	ds_read_b128 v[78:81], v1 offset:44480
	ds_read_b128 v[82:85], v1 offset:44496
	ds_read_b128 v[86:89], v1 offset:44512
	ds_read_b128 v[226:229], v1 offset:44528
	ds_read_b128 v[230:233], v1 offset:44544
	ds_read_b128 v[234:237], v1 offset:44560
	ds_read_b128 v[238:241], v1 offset:44576
	s_waitcnt lgkmcnt(0)
	v_fmac_f32_e32 v13, v45, v12
	v_pk_fma_f32 v[14:15], v[46:47], v[12:13], v[14:15] op_sel:[0,0,0] op_sel_hi:[1,0,1]
	v_pk_fma_f32 v[16:17], v[48:49], v[12:13], v[16:17] op_sel:[0,0,0] op_sel_hi:[1,0,1]
	v_pk_fma_f32 v[18:19], v[50:51], v[12:13], v[18:19] op_sel:[0,0,0] op_sel_hi:[1,0,1]
	v_pk_fma_f32 v[20:21], v[52:53], v[12:13], v[20:21] op_sel:[0,0,0] op_sel_hi:[1,0,1]
	v_pk_fma_f32 v[22:23], v[54:55], v[12:13], v[22:23] op_sel:[0,0,0] op_sel_hi:[1,0,1]
	v_pk_fma_f32 v[24:25], v[56:57], v[12:13], v[24:25] op_sel:[0,0,0] op_sel_hi:[1,0,1]
	v_pk_fma_f32 v[26:27], v[58:59], v[12:13], v[26:27] op_sel:[0,0,0] op_sel_hi:[1,0,1]
	v_pk_fma_f32 v[28:29], v[60:61], v[12:13], v[28:29] op_sel:[0,0,0] op_sel_hi:[1,0,1]
	v_pk_fma_f32 v[30:31], v[62:63], v[12:13], v[30:31] op_sel:[0,0,0] op_sel_hi:[1,0,1]
	v_pk_fma_f32 v[32:33], v[64:65], v[12:13], v[32:33] op_sel:[0,0,0] op_sel_hi:[1,0,1]
	v_pk_fma_f32 v[34:35], v[66:67], v[12:13], v[34:35] op_sel:[0,0,0] op_sel_hi:[1,0,1]
	v_pk_fma_f32 v[36:37], v[68:69], v[12:13], v[36:37] op_sel:[0,0,0] op_sel_hi:[1,0,1]
	v_pk_fma_f32 v[38:39], v[70:71], v[12:13], v[38:39] op_sel:[0,0,0] op_sel_hi:[1,0,1]
	v_pk_fma_f32 v[40:41], v[72:73], v[12:13], v[40:41] op_sel:[0,0,0] op_sel_hi:[1,0,1]
	ds_read_b128 v[46:49], v1 offset:44624
	ds_read_b128 v[50:53], v1 offset:44640
	ds_read_b128 v[54:57], v1 offset:44656
	ds_read_b128 v[58:61], v1 offset:44672
	ds_read_b128 v[62:65], v1 offset:44688
	ds_read_b128 v[66:69], v1 offset:44704
	ds_read_b128 v[70:73], v1 offset:44720
	s_waitcnt lgkmcnt(0)
	v_pk_fma_f32 v[14:15], v[78:79], v[12:13], v[14:15] op_sel:[0,1,0] op_sel_hi:[1,1,1]
	v_pk_fma_f32 v[16:17], v[80:81], v[12:13], v[16:17] op_sel:[0,1,0] op_sel_hi:[1,1,1]
	v_pk_fma_f32 v[18:19], v[82:83], v[12:13], v[18:19] op_sel:[0,1,0] op_sel_hi:[1,1,1]
	v_pk_fma_f32 v[20:21], v[84:85], v[12:13], v[20:21] op_sel:[0,1,0] op_sel_hi:[1,1,1]
	v_pk_fma_f32 v[22:23], v[86:87], v[12:13], v[22:23] op_sel:[0,1,0] op_sel_hi:[1,1,1]
	v_pk_fma_f32 v[24:25], v[88:89], v[12:13], v[24:25] op_sel:[0,1,0] op_sel_hi:[1,1,1]
	v_pk_fma_f32 v[26:27], v[226:227], v[12:13], v[26:27] op_sel:[0,1,0] op_sel_hi:[1,1,1]
	v_pk_fma_f32 v[28:29], v[228:229], v[12:13], v[28:29] op_sel:[0,1,0] op_sel_hi:[1,1,1]
	v_pk_fma_f32 v[30:31], v[230:231], v[12:13], v[30:31] op_sel:[0,1,0] op_sel_hi:[1,1,1]
	v_pk_fma_f32 v[32:33], v[232:233], v[12:13], v[32:33] op_sel:[0,1,0] op_sel_hi:[1,1,1]
	v_pk_fma_f32 v[34:35], v[234:235], v[12:13], v[34:35] op_sel:[0,1,0] op_sel_hi:[1,1,1]
	v_pk_fma_f32 v[36:37], v[236:237], v[12:13], v[36:37] op_sel:[0,1,0] op_sel_hi:[1,1,1]
	v_pk_fma_f32 v[38:39], v[238:239], v[12:13], v[38:39] op_sel:[0,1,0] op_sel_hi:[1,1,1]
	v_pk_fma_f32 v[40:41], v[240:241], v[12:13], v[40:41] op_sel:[0,1,0] op_sel_hi:[1,1,1]
	ds_read_b128 v[78:81], v1 offset:44768
	ds_read_b128 v[82:85], v1 offset:44784
	ds_read_b128 v[86:89], v1 offset:44800
	ds_read_b128 v[226:229], v1 offset:44816
	ds_read_b128 v[230:233], v1 offset:44832
	ds_read_b128 v[234:237], v1 offset:44848
	ds_read_b128 v[238:241], v1 offset:44864
	s_waitcnt lgkmcnt(0)
	v_fmac_f32_e32 v15, v47, v14
	v_pk_fma_f32 v[16:17], v[48:49], v[14:15], v[16:17] op_sel:[0,0,0] op_sel_hi:[1,0,1]
	v_pk_fma_f32 v[18:19], v[50:51], v[14:15], v[18:19] op_sel:[0,0,0] op_sel_hi:[1,0,1]
	v_pk_fma_f32 v[20:21], v[52:53], v[14:15], v[20:21] op_sel:[0,0,0] op_sel_hi:[1,0,1]
	v_pk_fma_f32 v[22:23], v[54:55], v[14:15], v[22:23] op_sel:[0,0,0] op_sel_hi:[1,0,1]
	v_pk_fma_f32 v[24:25], v[56:57], v[14:15], v[24:25] op_sel:[0,0,0] op_sel_hi:[1,0,1]
	v_pk_fma_f32 v[26:27], v[58:59], v[14:15], v[26:27] op_sel:[0,0,0] op_sel_hi:[1,0,1]
	v_pk_fma_f32 v[28:29], v[60:61], v[14:15], v[28:29] op_sel:[0,0,0] op_sel_hi:[1,0,1]
	v_pk_fma_f32 v[30:31], v[62:63], v[14:15], v[30:31] op_sel:[0,0,0] op_sel_hi:[1,0,1]
	v_pk_fma_f32 v[32:33], v[64:65], v[14:15], v[32:33] op_sel:[0,0,0] op_sel_hi:[1,0,1]
	v_pk_fma_f32 v[34:35], v[66:67], v[14:15], v[34:35] op_sel:[0,0,0] op_sel_hi:[1,0,1]
	v_pk_fma_f32 v[36:37], v[68:69], v[14:15], v[36:37] op_sel:[0,0,0] op_sel_hi:[1,0,1]
	v_pk_fma_f32 v[38:39], v[70:71], v[14:15], v[38:39] op_sel:[0,0,0] op_sel_hi:[1,0,1]
	v_pk_fma_f32 v[40:41], v[72:73], v[14:15], v[40:41] op_sel:[0,0,0] op_sel_hi:[1,0,1]
	ds_read_b128 v[46:49], v1 offset:44912
	ds_read_b128 v[50:53], v1 offset:44928
	ds_read_b128 v[54:57], v1 offset:44944
	ds_read_b128 v[58:61], v1 offset:44960
	ds_read_b128 v[62:65], v1 offset:44976
	ds_read_b128 v[66:69], v1 offset:44992
	ds_read_b128 v[70:73], v1 offset:45008
	s_waitcnt lgkmcnt(0)
	v_pk_fma_f32 v[16:17], v[80:81], v[14:15], v[16:17] op_sel:[0,1,0] op_sel_hi:[1,1,1]
	v_pk_fma_f32 v[18:19], v[82:83], v[14:15], v[18:19] op_sel:[0,1,0] op_sel_hi:[1,1,1]
	v_pk_fma_f32 v[20:21], v[84:85], v[14:15], v[20:21] op_sel:[0,1,0] op_sel_hi:[1,1,1]
	v_pk_fma_f32 v[22:23], v[86:87], v[14:15], v[22:23] op_sel:[0,1,0] op_sel_hi:[1,1,1]
	v_pk_fma_f32 v[24:25], v[88:89], v[14:15], v[24:25] op_sel:[0,1,0] op_sel_hi:[1,1,1]
	v_pk_fma_f32 v[26:27], v[226:227], v[14:15], v[26:27] op_sel:[0,1,0] op_sel_hi:[1,1,1]
	v_pk_fma_f32 v[28:29], v[228:229], v[14:15], v[28:29] op_sel:[0,1,0] op_sel_hi:[1,1,1]
	v_pk_fma_f32 v[30:31], v[230:231], v[14:15], v[30:31] op_sel:[0,1,0] op_sel_hi:[1,1,1]
	v_pk_fma_f32 v[32:33], v[232:233], v[14:15], v[32:33] op_sel:[0,1,0] op_sel_hi:[1,1,1]
	v_pk_fma_f32 v[34:35], v[234:235], v[14:15], v[34:35] op_sel:[0,1,0] op_sel_hi:[1,1,1]
	v_pk_fma_f32 v[36:37], v[236:237], v[14:15], v[36:37] op_sel:[0,1,0] op_sel_hi:[1,1,1]
	v_pk_fma_f32 v[38:39], v[238:239], v[14:15], v[38:39] op_sel:[0,1,0] op_sel_hi:[1,1,1]
	v_pk_fma_f32 v[40:41], v[240:241], v[14:15], v[40:41] op_sel:[0,1,0] op_sel_hi:[1,1,1]
	ds_read_b128 v[82:85], v1 offset:45072
	ds_read_b128 v[86:89], v1 offset:45088
	ds_read_b128 v[226:229], v1 offset:45104
	ds_read_b128 v[230:233], v1 offset:45120
	ds_read_b128 v[234:237], v1 offset:45136
	ds_read_b128 v[238:241], v1 offset:45152
	s_waitcnt lgkmcnt(0)
	v_fmac_f32_e32 v17, v49, v16
	v_pk_fma_f32 v[18:19], v[50:51], v[16:17], v[18:19] op_sel:[0,0,0] op_sel_hi:[1,0,1]
	v_pk_fma_f32 v[20:21], v[52:53], v[16:17], v[20:21] op_sel:[0,0,0] op_sel_hi:[1,0,1]
	v_pk_fma_f32 v[22:23], v[54:55], v[16:17], v[22:23] op_sel:[0,0,0] op_sel_hi:[1,0,1]
	v_pk_fma_f32 v[24:25], v[56:57], v[16:17], v[24:25] op_sel:[0,0,0] op_sel_hi:[1,0,1]
	v_pk_fma_f32 v[26:27], v[58:59], v[16:17], v[26:27] op_sel:[0,0,0] op_sel_hi:[1,0,1]
	v_pk_fma_f32 v[28:29], v[60:61], v[16:17], v[28:29] op_sel:[0,0,0] op_sel_hi:[1,0,1]
	v_pk_fma_f32 v[30:31], v[62:63], v[16:17], v[30:31] op_sel:[0,0,0] op_sel_hi:[1,0,1]
	v_pk_fma_f32 v[32:33], v[64:65], v[16:17], v[32:33] op_sel:[0,0,0] op_sel_hi:[1,0,1]
	v_pk_fma_f32 v[34:35], v[66:67], v[16:17], v[34:35] op_sel:[0,0,0] op_sel_hi:[1,0,1]
	v_pk_fma_f32 v[36:37], v[68:69], v[16:17], v[36:37] op_sel:[0,0,0] op_sel_hi:[1,0,1]
	v_pk_fma_f32 v[38:39], v[70:71], v[16:17], v[38:39] op_sel:[0,0,0] op_sel_hi:[1,0,1]
	v_pk_fma_f32 v[40:41], v[72:73], v[16:17], v[40:41] op_sel:[0,0,0] op_sel_hi:[1,0,1]
	ds_read_b128 v[50:53], v1 offset:45216
	ds_read_b128 v[54:57], v1 offset:45232
	ds_read_b128 v[58:61], v1 offset:45248
	ds_read_b128 v[62:65], v1 offset:45264
	ds_read_b128 v[66:69], v1 offset:45280
	ds_read_b128 v[70:73], v1 offset:45296
	s_waitcnt lgkmcnt(0)
	v_pk_fma_f32 v[18:19], v[82:83], v[16:17], v[18:19] op_sel:[0,1,0] op_sel_hi:[1,1,1]
	v_pk_fma_f32 v[20:21], v[84:85], v[16:17], v[20:21] op_sel:[0,1,0] op_sel_hi:[1,1,1]
	v_pk_fma_f32 v[22:23], v[86:87], v[16:17], v[22:23] op_sel:[0,1,0] op_sel_hi:[1,1,1]
	v_pk_fma_f32 v[24:25], v[88:89], v[16:17], v[24:25] op_sel:[0,1,0] op_sel_hi:[1,1,1]
	v_pk_fma_f32 v[26:27], v[226:227], v[16:17], v[26:27] op_sel:[0,1,0] op_sel_hi:[1,1,1]
	v_pk_fma_f32 v[28:29], v[228:229], v[16:17], v[28:29] op_sel:[0,1,0] op_sel_hi:[1,1,1]
	v_pk_fma_f32 v[30:31], v[230:231], v[16:17], v[30:31] op_sel:[0,1,0] op_sel_hi:[1,1,1]
	v_pk_fma_f32 v[32:33], v[232:233], v[16:17], v[32:33] op_sel:[0,1,0] op_sel_hi:[1,1,1]
	v_pk_fma_f32 v[34:35], v[234:235], v[16:17], v[34:35] op_sel:[0,1,0] op_sel_hi:[1,1,1]
	v_pk_fma_f32 v[36:37], v[236:237], v[16:17], v[36:37] op_sel:[0,1,0] op_sel_hi:[1,1,1]
	v_pk_fma_f32 v[38:39], v[238:239], v[16:17], v[38:39] op_sel:[0,1,0] op_sel_hi:[1,1,1]
	v_pk_fma_f32 v[40:41], v[240:241], v[16:17], v[40:41] op_sel:[0,1,0] op_sel_hi:[1,1,1]
	ds_read_b128 v[82:85], v1 offset:45360
	ds_read_b128 v[86:89], v1 offset:45376
	ds_read_b128 v[226:229], v1 offset:45392
	ds_read_b128 v[230:233], v1 offset:45408
	ds_read_b128 v[234:237], v1 offset:45424
	ds_read_b128 v[238:241], v1 offset:45440
	s_waitcnt lgkmcnt(0)
	v_fmac_f32_e32 v19, v51, v18
	v_pk_fma_f32 v[20:21], v[52:53], v[18:19], v[20:21] op_sel:[0,0,0] op_sel_hi:[1,0,1]
	v_pk_fma_f32 v[22:23], v[54:55], v[18:19], v[22:23] op_sel:[0,0,0] op_sel_hi:[1,0,1]
	v_pk_fma_f32 v[24:25], v[56:57], v[18:19], v[24:25] op_sel:[0,0,0] op_sel_hi:[1,0,1]
	v_pk_fma_f32 v[26:27], v[58:59], v[18:19], v[26:27] op_sel:[0,0,0] op_sel_hi:[1,0,1]
	v_pk_fma_f32 v[28:29], v[60:61], v[18:19], v[28:29] op_sel:[0,0,0] op_sel_hi:[1,0,1]
	v_pk_fma_f32 v[30:31], v[62:63], v[18:19], v[30:31] op_sel:[0,0,0] op_sel_hi:[1,0,1]
	v_pk_fma_f32 v[32:33], v[64:65], v[18:19], v[32:33] op_sel:[0,0,0] op_sel_hi:[1,0,1]
	v_pk_fma_f32 v[34:35], v[66:67], v[18:19], v[34:35] op_sel:[0,0,0] op_sel_hi:[1,0,1]
	v_pk_fma_f32 v[36:37], v[68:69], v[18:19], v[36:37] op_sel:[0,0,0] op_sel_hi:[1,0,1]
	v_pk_fma_f32 v[38:39], v[70:71], v[18:19], v[38:39] op_sel:[0,0,0] op_sel_hi:[1,0,1]
	v_pk_fma_f32 v[40:41], v[72:73], v[18:19], v[40:41] op_sel:[0,0,0] op_sel_hi:[1,0,1]
	ds_read_b128 v[50:53], v1 offset:45504
	ds_read_b128 v[54:57], v1 offset:45520
	ds_read_b128 v[58:61], v1 offset:45536
	ds_read_b128 v[62:65], v1 offset:45552
	ds_read_b128 v[66:69], v1 offset:45568
	ds_read_b128 v[70:73], v1 offset:45584
	s_waitcnt lgkmcnt(0)
	v_pk_fma_f32 v[20:21], v[84:85], v[18:19], v[20:21] op_sel:[0,1,0] op_sel_hi:[1,1,1]
	v_pk_fma_f32 v[22:23], v[86:87], v[18:19], v[22:23] op_sel:[0,1,0] op_sel_hi:[1,1,1]
	v_pk_fma_f32 v[24:25], v[88:89], v[18:19], v[24:25] op_sel:[0,1,0] op_sel_hi:[1,1,1]
	v_pk_fma_f32 v[26:27], v[226:227], v[18:19], v[26:27] op_sel:[0,1,0] op_sel_hi:[1,1,1]
	v_pk_fma_f32 v[28:29], v[228:229], v[18:19], v[28:29] op_sel:[0,1,0] op_sel_hi:[1,1,1]
	v_pk_fma_f32 v[30:31], v[230:231], v[18:19], v[30:31] op_sel:[0,1,0] op_sel_hi:[1,1,1]
	v_pk_fma_f32 v[32:33], v[232:233], v[18:19], v[32:33] op_sel:[0,1,0] op_sel_hi:[1,1,1]
	v_pk_fma_f32 v[34:35], v[234:235], v[18:19], v[34:35] op_sel:[0,1,0] op_sel_hi:[1,1,1]
	v_pk_fma_f32 v[36:37], v[236:237], v[18:19], v[36:37] op_sel:[0,1,0] op_sel_hi:[1,1,1]
	v_pk_fma_f32 v[38:39], v[238:239], v[18:19], v[38:39] op_sel:[0,1,0] op_sel_hi:[1,1,1]
	v_pk_fma_f32 v[40:41], v[240:241], v[18:19], v[40:41] op_sel:[0,1,0] op_sel_hi:[1,1,1]
	ds_read_b128 v[86:89], v1 offset:45664
	ds_read_b128 v[226:229], v1 offset:45680
	ds_read_b128 v[230:233], v1 offset:45696
	ds_read_b128 v[234:237], v1 offset:45712
	ds_read_b128 v[238:241], v1 offset:45728
	s_waitcnt lgkmcnt(0)
	v_fmac_f32_e32 v21, v53, v20
	v_pk_fma_f32 v[22:23], v[54:55], v[20:21], v[22:23] op_sel:[0,0,0] op_sel_hi:[1,0,1]
	v_pk_fma_f32 v[24:25], v[56:57], v[20:21], v[24:25] op_sel:[0,0,0] op_sel_hi:[1,0,1]
	v_pk_fma_f32 v[26:27], v[58:59], v[20:21], v[26:27] op_sel:[0,0,0] op_sel_hi:[1,0,1]
	v_pk_fma_f32 v[28:29], v[60:61], v[20:21], v[28:29] op_sel:[0,0,0] op_sel_hi:[1,0,1]
	v_pk_fma_f32 v[30:31], v[62:63], v[20:21], v[30:31] op_sel:[0,0,0] op_sel_hi:[1,0,1]
	v_pk_fma_f32 v[32:33], v[64:65], v[20:21], v[32:33] op_sel:[0,0,0] op_sel_hi:[1,0,1]
	v_pk_fma_f32 v[34:35], v[66:67], v[20:21], v[34:35] op_sel:[0,0,0] op_sel_hi:[1,0,1]
	v_pk_fma_f32 v[36:37], v[68:69], v[20:21], v[36:37] op_sel:[0,0,0] op_sel_hi:[1,0,1]
	v_pk_fma_f32 v[38:39], v[70:71], v[20:21], v[38:39] op_sel:[0,0,0] op_sel_hi:[1,0,1]
	v_pk_fma_f32 v[40:41], v[72:73], v[20:21], v[40:41] op_sel:[0,0,0] op_sel_hi:[1,0,1]
	ds_read_b128 v[54:57], v1 offset:45808
	ds_read_b128 v[58:61], v1 offset:45824
	ds_read_b128 v[62:65], v1 offset:45840
	ds_read_b128 v[66:69], v1 offset:45856
	ds_read_b128 v[70:73], v1 offset:45872
	s_waitcnt lgkmcnt(0)
	v_pk_fma_f32 v[22:23], v[86:87], v[20:21], v[22:23] op_sel:[0,1,0] op_sel_hi:[1,1,1]
	v_pk_fma_f32 v[24:25], v[88:89], v[20:21], v[24:25] op_sel:[0,1,0] op_sel_hi:[1,1,1]
	v_pk_fma_f32 v[26:27], v[226:227], v[20:21], v[26:27] op_sel:[0,1,0] op_sel_hi:[1,1,1]
	v_pk_fma_f32 v[28:29], v[228:229], v[20:21], v[28:29] op_sel:[0,1,0] op_sel_hi:[1,1,1]
	v_pk_fma_f32 v[30:31], v[230:231], v[20:21], v[30:31] op_sel:[0,1,0] op_sel_hi:[1,1,1]
	v_pk_fma_f32 v[32:33], v[232:233], v[20:21], v[32:33] op_sel:[0,1,0] op_sel_hi:[1,1,1]
	v_pk_fma_f32 v[34:35], v[234:235], v[20:21], v[34:35] op_sel:[0,1,0] op_sel_hi:[1,1,1]
	v_pk_fma_f32 v[36:37], v[236:237], v[20:21], v[36:37] op_sel:[0,1,0] op_sel_hi:[1,1,1]
	v_pk_fma_f32 v[38:39], v[238:239], v[20:21], v[38:39] op_sel:[0,1,0] op_sel_hi:[1,1,1]
	v_pk_fma_f32 v[40:41], v[240:241], v[20:21], v[40:41] op_sel:[0,1,0] op_sel_hi:[1,1,1]
	ds_read_b128 v[86:89], v1 offset:45952
	ds_read_b128 v[226:229], v1 offset:45968
	ds_read_b128 v[230:233], v1 offset:45984
	ds_read_b128 v[234:237], v1 offset:46000
	ds_read_b128 v[238:241], v1 offset:46016
	s_waitcnt lgkmcnt(0)
	v_fmac_f32_e32 v23, v55, v22
	v_pk_fma_f32 v[24:25], v[56:57], v[22:23], v[24:25] op_sel:[0,0,0] op_sel_hi:[1,0,1]
	v_pk_fma_f32 v[26:27], v[58:59], v[22:23], v[26:27] op_sel:[0,0,0] op_sel_hi:[1,0,1]
	v_pk_fma_f32 v[28:29], v[60:61], v[22:23], v[28:29] op_sel:[0,0,0] op_sel_hi:[1,0,1]
	v_pk_fma_f32 v[30:31], v[62:63], v[22:23], v[30:31] op_sel:[0,0,0] op_sel_hi:[1,0,1]
	v_pk_fma_f32 v[32:33], v[64:65], v[22:23], v[32:33] op_sel:[0,0,0] op_sel_hi:[1,0,1]
	v_pk_fma_f32 v[34:35], v[66:67], v[22:23], v[34:35] op_sel:[0,0,0] op_sel_hi:[1,0,1]
	v_pk_fma_f32 v[36:37], v[68:69], v[22:23], v[36:37] op_sel:[0,0,0] op_sel_hi:[1,0,1]
	v_pk_fma_f32 v[38:39], v[70:71], v[22:23], v[38:39] op_sel:[0,0,0] op_sel_hi:[1,0,1]
	v_pk_fma_f32 v[40:41], v[72:73], v[22:23], v[40:41] op_sel:[0,0,0] op_sel_hi:[1,0,1]
	ds_read_b128 v[54:57], v1 offset:46096
	ds_read_b128 v[58:61], v1 offset:46112
	ds_read_b128 v[62:65], v1 offset:46128
	ds_read_b128 v[66:69], v1 offset:46144
	ds_read_b128 v[70:73], v1 offset:46160
	s_waitcnt lgkmcnt(0)
	v_pk_fma_f32 v[24:25], v[88:89], v[22:23], v[24:25] op_sel:[0,1,0] op_sel_hi:[1,1,1]
	v_pk_fma_f32 v[26:27], v[226:227], v[22:23], v[26:27] op_sel:[0,1,0] op_sel_hi:[1,1,1]
	v_pk_fma_f32 v[28:29], v[228:229], v[22:23], v[28:29] op_sel:[0,1,0] op_sel_hi:[1,1,1]
	v_pk_fma_f32 v[30:31], v[230:231], v[22:23], v[30:31] op_sel:[0,1,0] op_sel_hi:[1,1,1]
	v_pk_fma_f32 v[32:33], v[232:233], v[22:23], v[32:33] op_sel:[0,1,0] op_sel_hi:[1,1,1]
	v_pk_fma_f32 v[34:35], v[234:235], v[22:23], v[34:35] op_sel:[0,1,0] op_sel_hi:[1,1,1]
	v_pk_fma_f32 v[36:37], v[236:237], v[22:23], v[36:37] op_sel:[0,1,0] op_sel_hi:[1,1,1]
	v_pk_fma_f32 v[38:39], v[238:239], v[22:23], v[38:39] op_sel:[0,1,0] op_sel_hi:[1,1,1]
	v_pk_fma_f32 v[40:41], v[240:241], v[22:23], v[40:41] op_sel:[0,1,0] op_sel_hi:[1,1,1]
	ds_read_b128 v[226:229], v1 offset:46256
	ds_read_b128 v[230:233], v1 offset:46272
	ds_read_b128 v[234:237], v1 offset:46288
	ds_read_b128 v[238:241], v1 offset:46304
	s_waitcnt lgkmcnt(0)
	v_fmac_f32_e32 v25, v57, v24
	v_pk_fma_f32 v[26:27], v[58:59], v[24:25], v[26:27] op_sel:[0,0,0] op_sel_hi:[1,0,1]
	v_pk_fma_f32 v[28:29], v[60:61], v[24:25], v[28:29] op_sel:[0,0,0] op_sel_hi:[1,0,1]
	v_pk_fma_f32 v[30:31], v[62:63], v[24:25], v[30:31] op_sel:[0,0,0] op_sel_hi:[1,0,1]
	v_pk_fma_f32 v[32:33], v[64:65], v[24:25], v[32:33] op_sel:[0,0,0] op_sel_hi:[1,0,1]
	v_pk_fma_f32 v[34:35], v[66:67], v[24:25], v[34:35] op_sel:[0,0,0] op_sel_hi:[1,0,1]
	v_pk_fma_f32 v[36:37], v[68:69], v[24:25], v[36:37] op_sel:[0,0,0] op_sel_hi:[1,0,1]
	v_pk_fma_f32 v[38:39], v[70:71], v[24:25], v[38:39] op_sel:[0,0,0] op_sel_hi:[1,0,1]
	v_pk_fma_f32 v[40:41], v[72:73], v[24:25], v[40:41] op_sel:[0,0,0] op_sel_hi:[1,0,1]
	ds_read_b128 v[58:61], v1 offset:46400
	ds_read_b128 v[62:65], v1 offset:46416
	ds_read_b128 v[66:69], v1 offset:46432
	ds_read_b128 v[70:73], v1 offset:46448
	s_waitcnt lgkmcnt(0)
	v_pk_fma_f32 v[26:27], v[226:227], v[24:25], v[26:27] op_sel:[0,1,0] op_sel_hi:[1,1,1]
	v_pk_fma_f32 v[28:29], v[228:229], v[24:25], v[28:29] op_sel:[0,1,0] op_sel_hi:[1,1,1]
	v_pk_fma_f32 v[30:31], v[230:231], v[24:25], v[30:31] op_sel:[0,1,0] op_sel_hi:[1,1,1]
	v_pk_fma_f32 v[32:33], v[232:233], v[24:25], v[32:33] op_sel:[0,1,0] op_sel_hi:[1,1,1]
	v_pk_fma_f32 v[34:35], v[234:235], v[24:25], v[34:35] op_sel:[0,1,0] op_sel_hi:[1,1,1]
	v_pk_fma_f32 v[36:37], v[236:237], v[24:25], v[36:37] op_sel:[0,1,0] op_sel_hi:[1,1,1]
	v_pk_fma_f32 v[38:39], v[238:239], v[24:25], v[38:39] op_sel:[0,1,0] op_sel_hi:[1,1,1]
	v_pk_fma_f32 v[40:41], v[240:241], v[24:25], v[40:41] op_sel:[0,1,0] op_sel_hi:[1,1,1]
	ds_read_b128 v[226:229], v1 offset:46544
	ds_read_b128 v[230:233], v1 offset:46560
	ds_read_b128 v[234:237], v1 offset:46576
	ds_read_b128 v[238:241], v1 offset:46592
	s_waitcnt lgkmcnt(0)
	v_fmac_f32_e32 v27, v59, v26
	v_pk_fma_f32 v[28:29], v[60:61], v[26:27], v[28:29] op_sel:[0,0,0] op_sel_hi:[1,0,1]
	v_pk_fma_f32 v[30:31], v[62:63], v[26:27], v[30:31] op_sel:[0,0,0] op_sel_hi:[1,0,1]
	v_pk_fma_f32 v[32:33], v[64:65], v[26:27], v[32:33] op_sel:[0,0,0] op_sel_hi:[1,0,1]
	v_pk_fma_f32 v[34:35], v[66:67], v[26:27], v[34:35] op_sel:[0,0,0] op_sel_hi:[1,0,1]
	v_pk_fma_f32 v[36:37], v[68:69], v[26:27], v[36:37] op_sel:[0,0,0] op_sel_hi:[1,0,1]
	v_pk_fma_f32 v[38:39], v[70:71], v[26:27], v[38:39] op_sel:[0,0,0] op_sel_hi:[1,0,1]
	v_pk_fma_f32 v[40:41], v[72:73], v[26:27], v[40:41] op_sel:[0,0,0] op_sel_hi:[1,0,1]
	ds_read_b128 v[58:61], v1 offset:46688
	ds_read_b128 v[62:65], v1 offset:46704
	ds_read_b128 v[66:69], v1 offset:46720
	ds_read_b128 v[70:73], v1 offset:46736
	s_waitcnt lgkmcnt(0)
	v_pk_fma_f32 v[28:29], v[228:229], v[26:27], v[28:29] op_sel:[0,1,0] op_sel_hi:[1,1,1]
	v_pk_fma_f32 v[30:31], v[230:231], v[26:27], v[30:31] op_sel:[0,1,0] op_sel_hi:[1,1,1]
	v_pk_fma_f32 v[32:33], v[232:233], v[26:27], v[32:33] op_sel:[0,1,0] op_sel_hi:[1,1,1]
	v_pk_fma_f32 v[34:35], v[234:235], v[26:27], v[34:35] op_sel:[0,1,0] op_sel_hi:[1,1,1]
	v_pk_fma_f32 v[36:37], v[236:237], v[26:27], v[36:37] op_sel:[0,1,0] op_sel_hi:[1,1,1]
	v_pk_fma_f32 v[38:39], v[238:239], v[26:27], v[38:39] op_sel:[0,1,0] op_sel_hi:[1,1,1]
	v_pk_fma_f32 v[40:41], v[240:241], v[26:27], v[40:41] op_sel:[0,1,0] op_sel_hi:[1,1,1]
	ds_read_b128 v[230:233], v1 offset:46848
	ds_read_b128 v[234:237], v1 offset:46864
	ds_read_b128 v[238:241], v1 offset:46880
	s_waitcnt lgkmcnt(0)
	v_fmac_f32_e32 v29, v61, v28
	v_pk_fma_f32 v[30:31], v[62:63], v[28:29], v[30:31] op_sel:[0,0,0] op_sel_hi:[1,0,1]
	v_pk_fma_f32 v[32:33], v[64:65], v[28:29], v[32:33] op_sel:[0,0,0] op_sel_hi:[1,0,1]
	v_pk_fma_f32 v[34:35], v[66:67], v[28:29], v[34:35] op_sel:[0,0,0] op_sel_hi:[1,0,1]
	v_pk_fma_f32 v[36:37], v[68:69], v[28:29], v[36:37] op_sel:[0,0,0] op_sel_hi:[1,0,1]
	v_pk_fma_f32 v[38:39], v[70:71], v[28:29], v[38:39] op_sel:[0,0,0] op_sel_hi:[1,0,1]
	v_pk_fma_f32 v[40:41], v[72:73], v[28:29], v[40:41] op_sel:[0,0,0] op_sel_hi:[1,0,1]
	ds_read_b128 v[62:65], v1 offset:46992
	ds_read_b128 v[66:69], v1 offset:47008
	ds_read_b128 v[70:73], v1 offset:47024
	s_waitcnt lgkmcnt(0)
	v_pk_fma_f32 v[30:31], v[230:231], v[28:29], v[30:31] op_sel:[0,1,0] op_sel_hi:[1,1,1]
	v_pk_fma_f32 v[32:33], v[232:233], v[28:29], v[32:33] op_sel:[0,1,0] op_sel_hi:[1,1,1]
	v_pk_fma_f32 v[34:35], v[234:235], v[28:29], v[34:35] op_sel:[0,1,0] op_sel_hi:[1,1,1]
	v_pk_fma_f32 v[36:37], v[236:237], v[28:29], v[36:37] op_sel:[0,1,0] op_sel_hi:[1,1,1]
	v_pk_fma_f32 v[38:39], v[238:239], v[28:29], v[38:39] op_sel:[0,1,0] op_sel_hi:[1,1,1]
	v_pk_fma_f32 v[40:41], v[240:241], v[28:29], v[40:41] op_sel:[0,1,0] op_sel_hi:[1,1,1]
	ds_read_b128 v[230:233], v1 offset:47136
	ds_read_b128 v[234:237], v1 offset:47152
	ds_read_b128 v[238:241], v1 offset:47168
	s_waitcnt lgkmcnt(0)
	v_fmac_f32_e32 v31, v63, v30
	v_pk_fma_f32 v[32:33], v[64:65], v[30:31], v[32:33] op_sel:[0,0,0] op_sel_hi:[1,0,1]
	v_pk_fma_f32 v[34:35], v[66:67], v[30:31], v[34:35] op_sel:[0,0,0] op_sel_hi:[1,0,1]
	v_pk_fma_f32 v[36:37], v[68:69], v[30:31], v[36:37] op_sel:[0,0,0] op_sel_hi:[1,0,1]
	v_pk_fma_f32 v[38:39], v[70:71], v[30:31], v[38:39] op_sel:[0,0,0] op_sel_hi:[1,0,1]
	v_pk_fma_f32 v[40:41], v[72:73], v[30:31], v[40:41] op_sel:[0,0,0] op_sel_hi:[1,0,1]
	ds_read_b128 v[62:65], v1 offset:47280
	ds_read_b128 v[66:69], v1 offset:47296
	ds_read_b128 v[70:73], v1 offset:47312
	s_waitcnt lgkmcnt(0)
	v_pk_fma_f32 v[32:33], v[232:233], v[30:31], v[32:33] op_sel:[0,1,0] op_sel_hi:[1,1,1]
	v_pk_fma_f32 v[34:35], v[234:235], v[30:31], v[34:35] op_sel:[0,1,0] op_sel_hi:[1,1,1]
	v_pk_fma_f32 v[36:37], v[236:237], v[30:31], v[36:37] op_sel:[0,1,0] op_sel_hi:[1,1,1]
	v_pk_fma_f32 v[38:39], v[238:239], v[30:31], v[38:39] op_sel:[0,1,0] op_sel_hi:[1,1,1]
	v_pk_fma_f32 v[40:41], v[240:241], v[30:31], v[40:41] op_sel:[0,1,0] op_sel_hi:[1,1,1]
	ds_read_b128 v[234:237], v1 offset:47440
	ds_read_b128 v[238:241], v1 offset:47456
	s_waitcnt lgkmcnt(0)
	v_fmac_f32_e32 v33, v65, v32
	v_pk_fma_f32 v[34:35], v[66:67], v[32:33], v[34:35] op_sel:[0,0,0] op_sel_hi:[1,0,1]
	v_pk_fma_f32 v[36:37], v[68:69], v[32:33], v[36:37] op_sel:[0,0,0] op_sel_hi:[1,0,1]
	v_pk_fma_f32 v[38:39], v[70:71], v[32:33], v[38:39] op_sel:[0,0,0] op_sel_hi:[1,0,1]
	v_pk_fma_f32 v[40:41], v[72:73], v[32:33], v[40:41] op_sel:[0,0,0] op_sel_hi:[1,0,1]
	ds_read_b128 v[66:69], v1 offset:47584
	ds_read_b128 v[70:73], v1 offset:47600
	s_waitcnt lgkmcnt(0)
	v_pk_fma_f32 v[34:35], v[234:235], v[32:33], v[34:35] op_sel:[0,1,0] op_sel_hi:[1,1,1]
	v_pk_fma_f32 v[36:37], v[236:237], v[32:33], v[36:37] op_sel:[0,1,0] op_sel_hi:[1,1,1]
	v_pk_fma_f32 v[38:39], v[238:239], v[32:33], v[38:39] op_sel:[0,1,0] op_sel_hi:[1,1,1]
	v_pk_fma_f32 v[40:41], v[240:241], v[32:33], v[40:41] op_sel:[0,1,0] op_sel_hi:[1,1,1]
	ds_read_b128 v[234:237], v1 offset:47728
	ds_read_b128 v[238:241], v1 offset:47744
	s_waitcnt lgkmcnt(0)
	v_fmac_f32_e32 v35, v67, v34
	v_pk_fma_f32 v[36:37], v[68:69], v[34:35], v[36:37] op_sel:[0,0,0] op_sel_hi:[1,0,1]
	v_pk_fma_f32 v[38:39], v[70:71], v[34:35], v[38:39] op_sel:[0,0,0] op_sel_hi:[1,0,1]
	v_pk_fma_f32 v[40:41], v[72:73], v[34:35], v[40:41] op_sel:[0,0,0] op_sel_hi:[1,0,1]
	ds_read_b128 v[66:69], v1 offset:47872
	ds_read_b128 v[70:73], v1 offset:47888
	s_waitcnt lgkmcnt(0)
	v_pk_fma_f32 v[36:37], v[236:237], v[34:35], v[36:37] op_sel:[0,1,0] op_sel_hi:[1,1,1]
	v_pk_fma_f32 v[38:39], v[238:239], v[34:35], v[38:39] op_sel:[0,1,0] op_sel_hi:[1,1,1]
	v_pk_fma_f32 v[40:41], v[240:241], v[34:35], v[40:41] op_sel:[0,1,0] op_sel_hi:[1,1,1]
	ds_read_b128 v[238:241], v1 offset:48032
	s_waitcnt lgkmcnt(0)
	v_fmac_f32_e32 v37, v69, v36
	v_pk_fma_f32 v[38:39], v[70:71], v[36:37], v[38:39] op_sel:[0,0,0] op_sel_hi:[1,0,1]
	v_pk_fma_f32 v[40:41], v[72:73], v[36:37], v[40:41] op_sel:[0,0,0] op_sel_hi:[1,0,1]
	ds_read_b128 v[70:73], v1 offset:48176
	s_waitcnt lgkmcnt(0)
	v_pk_fma_f32 v[38:39], v[238:239], v[36:37], v[38:39] op_sel:[0,1,0] op_sel_hi:[1,1,1]
	v_pk_fma_f32 v[40:41], v[240:241], v[36:37], v[40:41] op_sel:[0,1,0] op_sel_hi:[1,1,1]
	ds_read_b128 v[238:241], v1 offset:48320
	s_waitcnt lgkmcnt(0)
	v_fmac_f32_e32 v39, v71, v38
	v_pk_fma_f32 v[40:41], v[72:73], v[38:39], v[40:41] op_sel:[0,0,0] op_sel_hi:[1,0,1]
	ds_read_b128 v[70:73], v1 offset:48464
	s_waitcnt lgkmcnt(0)
	v_pk_fma_f32 v[40:41], v[240:241], v[38:39], v[40:41] op_sel:[0,1,0] op_sel_hi:[1,1,1]
	s_waitcnt lgkmcnt(0)
	v_fmac_f32_e32 v41, v73, v40
	ds_write_b32 v135, v10 offset:57856
	ds_write_b32 v135, v11 offset:58000
	ds_write_b32 v135, v12 offset:58144
	ds_write_b32 v135, v13 offset:58288
	ds_write_b32 v135, v14 offset:58432
	ds_write_b32 v135, v15 offset:58576
	ds_write_b32 v135, v16 offset:58720
	ds_write_b32 v135, v17 offset:58864
	ds_write_b32 v135, v18 offset:59008
	ds_write_b32 v135, v19 offset:59152
	ds_write_b32 v135, v20 offset:59296
	ds_write_b32 v135, v21 offset:59440
	ds_write_b32 v135, v22 offset:59584
	ds_write_b32 v135, v23 offset:59728
	ds_write_b32 v135, v24 offset:59872
	ds_write_b32 v135, v25 offset:60016
	ds_write_b32 v135, v26 offset:60160
	ds_write_b32 v135, v27 offset:60304
	ds_write_b32 v135, v28 offset:60448
	ds_write_b32 v135, v29 offset:60592
	ds_write_b32 v135, v30 offset:60736
	ds_write_b32 v135, v31 offset:60880
	ds_write_b32 v135, v32 offset:61024
	ds_write_b32 v135, v33 offset:61168
	ds_write_b32 v135, v34 offset:61312
	ds_write_b32 v135, v35 offset:61456
	ds_write_b32 v135, v36 offset:61600
	ds_write_b32 v135, v37 offset:61744
	ds_write_b32 v135, v38 offset:61888
	ds_write_b32 v135, v39 offset:62032
	ds_write_b32 v135, v40 offset:62176
	ds_write_b32 v135, v41 offset:62320
	s_mov_b32 exec_hi, -1
	s_branch .Ldc_b3
